# norm phases: context-row split-K partial sum software-pipelined over a 6-slot register ring
# speedup vs baseline: 1.0040x; 1.0034x over previous
.Lnp_a:
	s_add_i32 s14, s90, -1
	s_mov_b32 s13, 0
	s_mov_b32 s10, 0
	s_min_u32 s11, s14, 0
	s_lshl_b32 s12, s11, 20
	v_lshl_add_u64 v[148:149], v[110:111], 0, s[12:13]
	global_load_dwordx4 v[118:121], v[148:149], off offset:-2048
	global_load_dwordx4 v[122:125], v[148:149], off offset:-1024
	global_load_dwordx4 v[126:129], v[148:149], off
	global_load_dwordx4 v[130:133], v[148:149], off offset:1024
	s_min_u32 s11, s14, 1
	s_lshl_b32 s12, s11, 20
	v_lshl_add_u64 v[148:149], v[110:111], 0, s[12:13]
	global_load_dwordx4 v[88:91], v[148:149], off offset:-2048
	global_load_dwordx4 v[84:87], v[148:149], off offset:-1024
	global_load_dwordx4 v[80:83], v[148:149], off
	global_load_dwordx4 v[76:79], v[148:149], off offset:1024
	s_min_u32 s11, s14, 2
	s_lshl_b32 s12, s11, 20
	v_lshl_add_u64 v[148:149], v[110:111], 0, s[12:13]
	global_load_dwordx4 v[72:75], v[148:149], off offset:-2048
	global_load_dwordx4 v[68:71], v[148:149], off offset:-1024
	global_load_dwordx4 v[64:67], v[148:149], off
	global_load_dwordx4 v[60:63], v[148:149], off offset:1024
	s_min_u32 s11, s14, 3
	s_lshl_b32 s12, s11, 20
	v_lshl_add_u64 v[148:149], v[110:111], 0, s[12:13]
	global_load_dwordx4 v[44:47], v[148:149], off offset:-2048
	global_load_dwordx4 v[48:51], v[148:149], off offset:-1024
	global_load_dwordx4 v[52:55], v[148:149], off
	global_load_dwordx4 v[56:59], v[148:149], off offset:1024
	s_min_u32 s11, s14, 4
	s_lshl_b32 s12, s11, 20
	v_lshl_add_u64 v[148:149], v[110:111], 0, s[12:13]
	global_load_dwordx4 v[160:163], v[148:149], off offset:-2048
	global_load_dwordx4 v[164:167], v[148:149], off offset:-1024
	global_load_dwordx4 v[168:171], v[148:149], off
	global_load_dwordx4 v[172:175], v[148:149], off offset:1024
	s_min_u32 s11, s14, 5
	s_lshl_b32 s12, s11, 20
	v_lshl_add_u64 v[148:149], v[110:111], 0, s[12:13]
	global_load_dwordx4 v[240:243], v[148:149], off offset:-2048
	global_load_dwordx4 v[244:247], v[148:149], off offset:-1024
	global_load_dwordx4 v[248:251], v[148:149], off
	global_load_dwordx4 v[144:147], v[148:149], off offset:1024
.Lnp_a_loop:
	s_add_i32 s11, s10, 6
	s_cmp_lt_u32 s11, s90
	s_cbranch_scc0 .Lnp_a_last
	s_waitcnt vmcnt(20)
	v_pk_add_f32 v[32:33], v[32:33], v[120:121]
	v_pk_add_f32 v[30:31], v[30:31], v[118:119]
	v_pk_add_f32 v[28:29], v[28:29], v[124:125]
	v_pk_add_f32 v[26:27], v[26:27], v[122:123]
	v_pk_add_f32 v[24:25], v[24:25], v[128:129]
	v_pk_add_f32 v[22:23], v[22:23], v[126:127]
	v_pk_add_f32 v[20:21], v[20:21], v[132:133]
	v_pk_add_f32 v[18:19], v[18:19], v[130:131]
	s_add_i32 s11, s10, 6
	s_min_u32 s11, s11, s14
	s_lshl_b32 s12, s11, 20
	v_lshl_add_u64 v[148:149], v[110:111], 0, s[12:13]
	global_load_dwordx4 v[118:121], v[148:149], off offset:-2048
	global_load_dwordx4 v[122:125], v[148:149], off offset:-1024
	global_load_dwordx4 v[126:129], v[148:149], off
	global_load_dwordx4 v[130:133], v[148:149], off offset:1024
	s_waitcnt vmcnt(20)
	v_pk_add_f32 v[32:33], v[32:33], v[90:91]
	v_pk_add_f32 v[30:31], v[30:31], v[88:89]
	v_pk_add_f32 v[28:29], v[28:29], v[86:87]
	v_pk_add_f32 v[26:27], v[26:27], v[84:85]
	v_pk_add_f32 v[24:25], v[24:25], v[82:83]
	v_pk_add_f32 v[22:23], v[22:23], v[80:81]
	v_pk_add_f32 v[20:21], v[20:21], v[78:79]
	v_pk_add_f32 v[18:19], v[18:19], v[76:77]
	s_add_i32 s11, s10, 7
	s_min_u32 s11, s11, s14
	s_lshl_b32 s12, s11, 20
	v_lshl_add_u64 v[148:149], v[110:111], 0, s[12:13]
	global_load_dwordx4 v[88:91], v[148:149], off offset:-2048
	global_load_dwordx4 v[84:87], v[148:149], off offset:-1024
	global_load_dwordx4 v[80:83], v[148:149], off
	global_load_dwordx4 v[76:79], v[148:149], off offset:1024
	s_waitcnt vmcnt(20)
	v_pk_add_f32 v[32:33], v[32:33], v[74:75]
	v_pk_add_f32 v[30:31], v[30:31], v[72:73]
	v_pk_add_f32 v[28:29], v[28:29], v[70:71]
	v_pk_add_f32 v[26:27], v[26:27], v[68:69]
	v_pk_add_f32 v[24:25], v[24:25], v[66:67]
	v_pk_add_f32 v[22:23], v[22:23], v[64:65]
	v_pk_add_f32 v[20:21], v[20:21], v[62:63]
	v_pk_add_f32 v[18:19], v[18:19], v[60:61]
	s_add_i32 s11, s10, 8
	s_min_u32 s11, s11, s14
	s_lshl_b32 s12, s11, 20
	v_lshl_add_u64 v[148:149], v[110:111], 0, s[12:13]
	global_load_dwordx4 v[72:75], v[148:149], off offset:-2048
	global_load_dwordx4 v[68:71], v[148:149], off offset:-1024
	global_load_dwordx4 v[64:67], v[148:149], off
	global_load_dwordx4 v[60:63], v[148:149], off offset:1024
	s_waitcnt vmcnt(20)
	v_pk_add_f32 v[32:33], v[32:33], v[46:47]
	v_pk_add_f32 v[30:31], v[30:31], v[44:45]
	v_pk_add_f32 v[28:29], v[28:29], v[50:51]
	v_pk_add_f32 v[26:27], v[26:27], v[48:49]
	v_pk_add_f32 v[24:25], v[24:25], v[54:55]
	v_pk_add_f32 v[22:23], v[22:23], v[52:53]
	v_pk_add_f32 v[20:21], v[20:21], v[58:59]
	v_pk_add_f32 v[18:19], v[18:19], v[56:57]
	s_add_i32 s11, s10, 9
	s_min_u32 s11, s11, s14
	s_lshl_b32 s12, s11, 20
	v_lshl_add_u64 v[148:149], v[110:111], 0, s[12:13]
	global_load_dwordx4 v[44:47], v[148:149], off offset:-2048
	global_load_dwordx4 v[48:51], v[148:149], off offset:-1024
	global_load_dwordx4 v[52:55], v[148:149], off
	global_load_dwordx4 v[56:59], v[148:149], off offset:1024
	s_waitcnt vmcnt(20)
	v_pk_add_f32 v[32:33], v[32:33], v[162:163]
	v_pk_add_f32 v[30:31], v[30:31], v[160:161]
	v_pk_add_f32 v[28:29], v[28:29], v[166:167]
	v_pk_add_f32 v[26:27], v[26:27], v[164:165]
	v_pk_add_f32 v[24:25], v[24:25], v[170:171]
	v_pk_add_f32 v[22:23], v[22:23], v[168:169]
	v_pk_add_f32 v[20:21], v[20:21], v[174:175]
	v_pk_add_f32 v[18:19], v[18:19], v[172:173]
	s_add_i32 s11, s10, 10
	s_min_u32 s11, s11, s14
	s_lshl_b32 s12, s11, 20
	v_lshl_add_u64 v[148:149], v[110:111], 0, s[12:13]
	global_load_dwordx4 v[160:163], v[148:149], off offset:-2048
	global_load_dwordx4 v[164:167], v[148:149], off offset:-1024
	global_load_dwordx4 v[168:171], v[148:149], off
	global_load_dwordx4 v[172:175], v[148:149], off offset:1024
	s_waitcnt vmcnt(20)
	v_pk_add_f32 v[32:33], v[32:33], v[242:243]
	v_pk_add_f32 v[30:31], v[30:31], v[240:241]
	v_pk_add_f32 v[28:29], v[28:29], v[246:247]
	v_pk_add_f32 v[26:27], v[26:27], v[244:245]
	v_pk_add_f32 v[24:25], v[24:25], v[250:251]
	v_pk_add_f32 v[22:23], v[22:23], v[248:249]
	v_pk_add_f32 v[20:21], v[20:21], v[146:147]
	v_pk_add_f32 v[18:19], v[18:19], v[144:145]
	s_add_i32 s11, s10, 11
	s_min_u32 s11, s11, s14
	s_lshl_b32 s12, s11, 20
	v_lshl_add_u64 v[148:149], v[110:111], 0, s[12:13]
	global_load_dwordx4 v[240:243], v[148:149], off offset:-2048
	global_load_dwordx4 v[244:247], v[148:149], off offset:-1024
	global_load_dwordx4 v[248:251], v[148:149], off
	global_load_dwordx4 v[144:147], v[148:149], off offset:1024
	s_add_i32 s10, s10, 6
	s_branch .Lnp_a_loop
.Lnp_a_last:
	s_waitcnt vmcnt(20)
	v_pk_add_f32 v[32:33], v[32:33], v[120:121]
	v_pk_add_f32 v[30:31], v[30:31], v[118:119]
	v_pk_add_f32 v[28:29], v[28:29], v[124:125]
	v_pk_add_f32 v[26:27], v[26:27], v[122:123]
	v_pk_add_f32 v[24:25], v[24:25], v[128:129]
	v_pk_add_f32 v[22:23], v[22:23], v[126:127]
	v_pk_add_f32 v[20:21], v[20:21], v[132:133]
	v_pk_add_f32 v[18:19], v[18:19], v[130:131]
	s_add_i32 s11, s10, 1
	s_cmp_lt_u32 s11, s90
	s_cbranch_scc0 .Lnp_a_done
	s_waitcnt vmcnt(16)
	v_pk_add_f32 v[32:33], v[32:33], v[90:91]
	v_pk_add_f32 v[30:31], v[30:31], v[88:89]
	v_pk_add_f32 v[28:29], v[28:29], v[86:87]
	v_pk_add_f32 v[26:27], v[26:27], v[84:85]
	v_pk_add_f32 v[24:25], v[24:25], v[82:83]
	v_pk_add_f32 v[22:23], v[22:23], v[80:81]
	v_pk_add_f32 v[20:21], v[20:21], v[78:79]
	v_pk_add_f32 v[18:19], v[18:19], v[76:77]
	s_add_i32 s11, s10, 2
	s_cmp_lt_u32 s11, s90
	s_cbranch_scc0 .Lnp_a_done
	s_waitcnt vmcnt(12)
	v_pk_add_f32 v[32:33], v[32:33], v[74:75]
	v_pk_add_f32 v[30:31], v[30:31], v[72:73]
	v_pk_add_f32 v[28:29], v[28:29], v[70:71]
	v_pk_add_f32 v[26:27], v[26:27], v[68:69]
	v_pk_add_f32 v[24:25], v[24:25], v[66:67]
	v_pk_add_f32 v[22:23], v[22:23], v[64:65]
	v_pk_add_f32 v[20:21], v[20:21], v[62:63]
	v_pk_add_f32 v[18:19], v[18:19], v[60:61]
	s_add_i32 s11, s10, 3
	s_cmp_lt_u32 s11, s90
	s_cbranch_scc0 .Lnp_a_done
	s_waitcnt vmcnt(8)
	v_pk_add_f32 v[32:33], v[32:33], v[46:47]
	v_pk_add_f32 v[30:31], v[30:31], v[44:45]
	v_pk_add_f32 v[28:29], v[28:29], v[50:51]
	v_pk_add_f32 v[26:27], v[26:27], v[48:49]
	v_pk_add_f32 v[24:25], v[24:25], v[54:55]
	v_pk_add_f32 v[22:23], v[22:23], v[52:53]
	v_pk_add_f32 v[20:21], v[20:21], v[58:59]
	v_pk_add_f32 v[18:19], v[18:19], v[56:57]
	s_add_i32 s11, s10, 4
	s_cmp_lt_u32 s11, s90
	s_cbranch_scc0 .Lnp_a_done
	s_waitcnt vmcnt(4)
	v_pk_add_f32 v[32:33], v[32:33], v[162:163]
	v_pk_add_f32 v[30:31], v[30:31], v[160:161]
	v_pk_add_f32 v[28:29], v[28:29], v[166:167]
	v_pk_add_f32 v[26:27], v[26:27], v[164:165]
	v_pk_add_f32 v[24:25], v[24:25], v[170:171]
	v_pk_add_f32 v[22:23], v[22:23], v[168:169]
	v_pk_add_f32 v[20:21], v[20:21], v[174:175]
	v_pk_add_f32 v[18:19], v[18:19], v[172:173]
	s_add_i32 s11, s10, 5
	s_cmp_lt_u32 s11, s90
	s_cbranch_scc0 .Lnp_a_done
	s_waitcnt vmcnt(0)
	v_pk_add_f32 v[32:33], v[32:33], v[242:243]
	v_pk_add_f32 v[30:31], v[30:31], v[240:241]
	v_pk_add_f32 v[28:29], v[28:29], v[246:247]
	v_pk_add_f32 v[26:27], v[26:27], v[244:245]
	v_pk_add_f32 v[24:25], v[24:25], v[250:251]
	v_pk_add_f32 v[22:23], v[22:23], v[248:249]
	v_pk_add_f32 v[20:21], v[20:21], v[146:147]
	v_pk_add_f32 v[18:19], v[18:19], v[144:145]
.Lnp_a_done:
	s_waitcnt vmcnt(0)
	s_branch .LBB0_238

.Lnp_b:
	s_add_i32 s14, s91, -1
	s_mov_b32 s13, 0
	s_mov_b32 s10, 0
	s_min_u32 s11, s14, 0
	s_lshl_b32 s12, s11, 20
	v_lshl_add_u64 v[148:149], v[116:117], 0, s[12:13]
	global_load_dwordx4 v[124:127], v[148:149], off offset:-2048
	global_load_dwordx4 v[128:131], v[148:149], off offset:-1024
	global_load_dwordx4 v[132:135], v[148:149], off
	global_load_dwordx4 v[136:139], v[148:149], off offset:1024
	s_min_u32 s11, s14, 1
	s_lshl_b32 s12, s11, 20
	v_lshl_add_u64 v[148:149], v[116:117], 0, s[12:13]
	global_load_dwordx4 v[94:97], v[148:149], off offset:-2048
	global_load_dwordx4 v[90:93], v[148:149], off offset:-1024
	global_load_dwordx4 v[86:89], v[148:149], off
	global_load_dwordx4 v[82:85], v[148:149], off offset:1024
	s_min_u32 s11, s14, 2
	s_lshl_b32 s12, s11, 20
	v_lshl_add_u64 v[148:149], v[116:117], 0, s[12:13]
	global_load_dwordx4 v[78:81], v[148:149], off offset:-2048
	global_load_dwordx4 v[74:77], v[148:149], off offset:-1024
	global_load_dwordx4 v[70:73], v[148:149], off
	global_load_dwordx4 v[66:69], v[148:149], off offset:1024
	s_min_u32 s11, s14, 3
	s_lshl_b32 s12, s11, 20
	v_lshl_add_u64 v[148:149], v[116:117], 0, s[12:13]
	global_load_dwordx4 v[50:53], v[148:149], off offset:-2048
	global_load_dwordx4 v[54:57], v[148:149], off offset:-1024
	global_load_dwordx4 v[58:61], v[148:149], off
	global_load_dwordx4 v[62:65], v[148:149], off offset:1024
	s_min_u32 s11, s14, 4
	s_lshl_b32 s12, s11, 20
	v_lshl_add_u64 v[148:149], v[116:117], 0, s[12:13]
	global_load_dwordx4 v[160:163], v[148:149], off offset:-2048
	global_load_dwordx4 v[164:167], v[148:149], off offset:-1024
	global_load_dwordx4 v[168:171], v[148:149], off
	global_load_dwordx4 v[172:175], v[148:149], off offset:1024
	s_min_u32 s11, s14, 5
	s_lshl_b32 s12, s11, 20
	v_lshl_add_u64 v[148:149], v[116:117], 0, s[12:13]
	global_load_dwordx4 v[240:243], v[148:149], off offset:-2048
	global_load_dwordx4 v[244:247], v[148:149], off offset:-1024
	global_load_dwordx4 v[248:251], v[148:149], off
	global_load_dwordx4 v[144:147], v[148:149], off offset:1024
.Lnp_b_loop:
	s_add_i32 s11, s10, 6
	s_cmp_lt_u32 s11, s91
	s_cbranch_scc0 .Lnp_b_last
	s_waitcnt vmcnt(20)
	v_pk_add_f32 v[32:33], v[32:33], v[126:127]
	v_pk_add_f32 v[30:31], v[30:31], v[124:125]
	v_pk_add_f32 v[28:29], v[28:29], v[130:131]
	v_pk_add_f32 v[26:27], v[26:27], v[128:129]
	v_pk_add_f32 v[24:25], v[24:25], v[134:135]
	v_pk_add_f32 v[22:23], v[22:23], v[132:133]
	v_pk_add_f32 v[20:21], v[20:21], v[138:139]
	v_pk_add_f32 v[18:19], v[18:19], v[136:137]
	s_add_i32 s11, s10, 6
	s_min_u32 s11, s11, s14
	s_lshl_b32 s12, s11, 20
	v_lshl_add_u64 v[148:149], v[116:117], 0, s[12:13]
	global_load_dwordx4 v[124:127], v[148:149], off offset:-2048
	global_load_dwordx4 v[128:131], v[148:149], off offset:-1024
	global_load_dwordx4 v[132:135], v[148:149], off
	global_load_dwordx4 v[136:139], v[148:149], off offset:1024
	s_waitcnt vmcnt(20)
	v_pk_add_f32 v[32:33], v[32:33], v[96:97]
	v_pk_add_f32 v[30:31], v[30:31], v[94:95]
	v_pk_add_f32 v[28:29], v[28:29], v[92:93]
	v_pk_add_f32 v[26:27], v[26:27], v[90:91]
	v_pk_add_f32 v[24:25], v[24:25], v[88:89]
	v_pk_add_f32 v[22:23], v[22:23], v[86:87]
	v_pk_add_f32 v[20:21], v[20:21], v[84:85]
	v_pk_add_f32 v[18:19], v[18:19], v[82:83]
	s_add_i32 s11, s10, 7
	s_min_u32 s11, s11, s14
	s_lshl_b32 s12, s11, 20
	v_lshl_add_u64 v[148:149], v[116:117], 0, s[12:13]
	global_load_dwordx4 v[94:97], v[148:149], off offset:-2048
	global_load_dwordx4 v[90:93], v[148:149], off offset:-1024
	global_load_dwordx4 v[86:89], v[148:149], off
	global_load_dwordx4 v[82:85], v[148:149], off offset:1024
	s_waitcnt vmcnt(20)
	v_pk_add_f32 v[32:33], v[32:33], v[80:81]
	v_pk_add_f32 v[30:31], v[30:31], v[78:79]
	v_pk_add_f32 v[28:29], v[28:29], v[76:77]
	v_pk_add_f32 v[26:27], v[26:27], v[74:75]
	v_pk_add_f32 v[24:25], v[24:25], v[72:73]
	v_pk_add_f32 v[22:23], v[22:23], v[70:71]
	v_pk_add_f32 v[20:21], v[20:21], v[68:69]
	v_pk_add_f32 v[18:19], v[18:19], v[66:67]
	s_add_i32 s11, s10, 8
	s_min_u32 s11, s11, s14
	s_lshl_b32 s12, s11, 20
	v_lshl_add_u64 v[148:149], v[116:117], 0, s[12:13]
	global_load_dwordx4 v[78:81], v[148:149], off offset:-2048
	global_load_dwordx4 v[74:77], v[148:149], off offset:-1024
	global_load_dwordx4 v[70:73], v[148:149], off
	global_load_dwordx4 v[66:69], v[148:149], off offset:1024
	s_waitcnt vmcnt(20)
	v_pk_add_f32 v[32:33], v[32:33], v[52:53]
	v_pk_add_f32 v[30:31], v[30:31], v[50:51]
	v_pk_add_f32 v[28:29], v[28:29], v[56:57]
	v_pk_add_f32 v[26:27], v[26:27], v[54:55]
	v_pk_add_f32 v[24:25], v[24:25], v[60:61]
	v_pk_add_f32 v[22:23], v[22:23], v[58:59]
	v_pk_add_f32 v[20:21], v[20:21], v[64:65]
	v_pk_add_f32 v[18:19], v[18:19], v[62:63]
	s_add_i32 s11, s10, 9
	s_min_u32 s11, s11, s14
	s_lshl_b32 s12, s11, 20
	v_lshl_add_u64 v[148:149], v[116:117], 0, s[12:13]
	global_load_dwordx4 v[50:53], v[148:149], off offset:-2048
	global_load_dwordx4 v[54:57], v[148:149], off offset:-1024
	global_load_dwordx4 v[58:61], v[148:149], off
	global_load_dwordx4 v[62:65], v[148:149], off offset:1024
	s_waitcnt vmcnt(20)
	v_pk_add_f32 v[32:33], v[32:33], v[162:163]
	v_pk_add_f32 v[30:31], v[30:31], v[160:161]
	v_pk_add_f32 v[28:29], v[28:29], v[166:167]
	v_pk_add_f32 v[26:27], v[26:27], v[164:165]
	v_pk_add_f32 v[24:25], v[24:25], v[170:171]
	v_pk_add_f32 v[22:23], v[22:23], v[168:169]
	v_pk_add_f32 v[20:21], v[20:21], v[174:175]
	v_pk_add_f32 v[18:19], v[18:19], v[172:173]
	s_add_i32 s11, s10, 10
	s_min_u32 s11, s11, s14
	s_lshl_b32 s12, s11, 20
	v_lshl_add_u64 v[148:149], v[116:117], 0, s[12:13]
	global_load_dwordx4 v[160:163], v[148:149], off offset:-2048
	global_load_dwordx4 v[164:167], v[148:149], off offset:-1024
	global_load_dwordx4 v[168:171], v[148:149], off
	global_load_dwordx4 v[172:175], v[148:149], off offset:1024
	s_waitcnt vmcnt(20)
	v_pk_add_f32 v[32:33], v[32:33], v[242:243]
	v_pk_add_f32 v[30:31], v[30:31], v[240:241]
	v_pk_add_f32 v[28:29], v[28:29], v[246:247]
	v_pk_add_f32 v[26:27], v[26:27], v[244:245]
	v_pk_add_f32 v[24:25], v[24:25], v[250:251]
	v_pk_add_f32 v[22:23], v[22:23], v[248:249]
	v_pk_add_f32 v[20:21], v[20:21], v[146:147]
	v_pk_add_f32 v[18:19], v[18:19], v[144:145]
	s_add_i32 s11, s10, 11
	s_min_u32 s11, s11, s14
	s_lshl_b32 s12, s11, 20
	v_lshl_add_u64 v[148:149], v[116:117], 0, s[12:13]
	global_load_dwordx4 v[240:243], v[148:149], off offset:-2048
	global_load_dwordx4 v[244:247], v[148:149], off offset:-1024
	global_load_dwordx4 v[248:251], v[148:149], off
	global_load_dwordx4 v[144:147], v[148:149], off offset:1024
	s_add_i32 s10, s10, 6
	s_branch .Lnp_b_loop
.Lnp_b_last:
	s_waitcnt vmcnt(20)
	v_pk_add_f32 v[32:33], v[32:33], v[126:127]
	v_pk_add_f32 v[30:31], v[30:31], v[124:125]
	v_pk_add_f32 v[28:29], v[28:29], v[130:131]
	v_pk_add_f32 v[26:27], v[26:27], v[128:129]
	v_pk_add_f32 v[24:25], v[24:25], v[134:135]
	v_pk_add_f32 v[22:23], v[22:23], v[132:133]
	v_pk_add_f32 v[20:21], v[20:21], v[138:139]
	v_pk_add_f32 v[18:19], v[18:19], v[136:137]
	s_add_i32 s11, s10, 1
	s_cmp_lt_u32 s11, s91
	s_cbranch_scc0 .Lnp_b_done
	s_waitcnt vmcnt(16)
	v_pk_add_f32 v[32:33], v[32:33], v[96:97]
	v_pk_add_f32 v[30:31], v[30:31], v[94:95]
	v_pk_add_f32 v[28:29], v[28:29], v[92:93]
	v_pk_add_f32 v[26:27], v[26:27], v[90:91]
	v_pk_add_f32 v[24:25], v[24:25], v[88:89]
	v_pk_add_f32 v[22:23], v[22:23], v[86:87]
	v_pk_add_f32 v[20:21], v[20:21], v[84:85]
	v_pk_add_f32 v[18:19], v[18:19], v[82:83]
	s_add_i32 s11, s10, 2
	s_cmp_lt_u32 s11, s91
	s_cbranch_scc0 .Lnp_b_done
	s_waitcnt vmcnt(12)
	v_pk_add_f32 v[32:33], v[32:33], v[80:81]
	v_pk_add_f32 v[30:31], v[30:31], v[78:79]
	v_pk_add_f32 v[28:29], v[28:29], v[76:77]
	v_pk_add_f32 v[26:27], v[26:27], v[74:75]
	v_pk_add_f32 v[24:25], v[24:25], v[72:73]
	v_pk_add_f32 v[22:23], v[22:23], v[70:71]
	v_pk_add_f32 v[20:21], v[20:21], v[68:69]
	v_pk_add_f32 v[18:19], v[18:19], v[66:67]
	s_add_i32 s11, s10, 3
	s_cmp_lt_u32 s11, s91
	s_cbranch_scc0 .Lnp_b_done
	s_waitcnt vmcnt(8)
	v_pk_add_f32 v[32:33], v[32:33], v[52:53]
	v_pk_add_f32 v[30:31], v[30:31], v[50:51]
	v_pk_add_f32 v[28:29], v[28:29], v[56:57]
	v_pk_add_f32 v[26:27], v[26:27], v[54:55]
	v_pk_add_f32 v[24:25], v[24:25], v[60:61]
	v_pk_add_f32 v[22:23], v[22:23], v[58:59]
	v_pk_add_f32 v[20:21], v[20:21], v[64:65]
	v_pk_add_f32 v[18:19], v[18:19], v[62:63]
	s_add_i32 s11, s10, 4
	s_cmp_lt_u32 s11, s91
	s_cbranch_scc0 .Lnp_b_done
	s_waitcnt vmcnt(4)
	v_pk_add_f32 v[32:33], v[32:33], v[162:163]
	v_pk_add_f32 v[30:31], v[30:31], v[160:161]
	v_pk_add_f32 v[28:29], v[28:29], v[166:167]
	v_pk_add_f32 v[26:27], v[26:27], v[164:165]
	v_pk_add_f32 v[24:25], v[24:25], v[170:171]
	v_pk_add_f32 v[22:23], v[22:23], v[168:169]
	v_pk_add_f32 v[20:21], v[20:21], v[174:175]
	v_pk_add_f32 v[18:19], v[18:19], v[172:173]
	s_add_i32 s11, s10, 5
	s_cmp_lt_u32 s11, s91
	s_cbranch_scc0 .Lnp_b_done
	s_waitcnt vmcnt(0)
	v_pk_add_f32 v[32:33], v[32:33], v[242:243]
	v_pk_add_f32 v[30:31], v[30:31], v[240:241]
	v_pk_add_f32 v[28:29], v[28:29], v[246:247]
	v_pk_add_f32 v[26:27], v[26:27], v[244:245]
	v_pk_add_f32 v[24:25], v[24:25], v[250:251]
	v_pk_add_f32 v[22:23], v[22:23], v[248:249]
	v_pk_add_f32 v[20:21], v[20:21], v[146:147]
	v_pk_add_f32 v[18:19], v[18:19], v[144:145]
